# grid barrier: non-leader workgroups poll the top-level generation word directly, per-XCD generation hop removed
# speedup vs baseline: 1.0130x; 1.0062x over previous
.LBB0_131:
	s_or_b64 exec, exec, s[8:9]
	v_cvt_f32_u32_e32 v4, v2
	s_waitcnt vmcnt(0)
	v_readfirstlane_b32 s3, v3
	v_sub_u32_e32 v3, 0, v2
	v_rcp_iflag_f32_e32 v4, v4
	v_add_u32_e32 v5, s3, v1
	v_mul_f32_e32 v4, 0x4f7ffffe, v4
	v_cvt_u32_f32_e32 v4, v4
	v_mul_lo_u32 v1, v3, v4
	v_mul_hi_u32 v1, v4, v1
	v_add_u32_e32 v1, v4, v1
	v_mul_hi_u32 v1, v5, v1
	v_mul_lo_u32 v3, v1, v2
	v_sub_u32_e32 v3, v5, v3
	v_add_u32_e32 v4, 1, v1
	v_cmp_ge_u32_e32 vcc, v3, v2
	s_nop 1
	v_cndmask_b32_e32 v1, v1, v4, vcc
	v_sub_u32_e32 v4, v3, v2
	v_cndmask_b32_e32 v3, v3, v4, vcc
	v_add_u32_e32 v4, 1, v1
	v_cmp_ge_u32_e32 vcc, v3, v2
	v_add_u32_e32 v3, 1, v5
	s_nop 0
	v_cndmask_b32_e32 v1, v1, v4, vcc
	v_mul_lo_u32 v4, v2, v1
	v_add_u32_e32 v2, v4, v2
	v_cmp_ne_u32_e32 vcc, v3, v2
	s_and_saveexec_b64 s[6:7], vcc
	s_xor_b64 s[6:7], exec, s[6:7]
	s_cbranch_execz .LBB0_145
	s_waitcnt lgkmcnt(0)
	v_mov_b32_e32 v0, 0x35400
	global_load_dword v0, v0, s[28:29] offset:256 sc1
	s_add_u32 s18, s28, 0x35500
	s_addc_u32 s19, s29, 0
	s_waitcnt vmcnt(0)
	v_cmp_eq_u32_e32 vcc, v0, v1
	s_and_saveexec_b64 s[8:9], vcc
	s_cbranch_execz .LBB0_144
	s_add_u32 s12, s28, 0x32200
	s_addc_u32 s13, s29, 0
	s_mov_b32 s3, 1
	s_mov_b64 s[22:23], 0
	v_mov_b32_e32 v0, 0
	s_branch .LBB0_135

.LBB0_162:
	s_or_b64 exec, exec, s[6:7]
	s_mov_b64 s[6:7], exec
	v_mbcnt_lo_u32_b32 v0, s6, 0
	v_mbcnt_hi_u32_b32 v0, s7, v0
	v_cmp_eq_u32_e32 vcc, 0, v0
	s_waitcnt vmcnt(0)
	buffer_inv sc1
	s_and_saveexec_b64 s[8:9], vcc
	s_cbranch_execz .LBB0_164
	s_bcnt1_i32_b64 s3, s[6:7]
	v_mov_b32_e32 v0, 0x2000
	v_mov_b32_e32 v1, s3
.LBB0_164:
	s_or_b64 exec, exec, s[8:9]
	s_waitcnt vmcnt(0)

.LBB0_229:
	s_or_b64 exec, exec, s[6:7]
	s_mov_b64 s[6:7], exec
	v_mbcnt_lo_u32_b32 v0, s6, 0
	v_mbcnt_hi_u32_b32 v0, s7, v0
	v_cmp_eq_u32_e32 vcc, 0, v0
	s_waitcnt vmcnt(0)
	buffer_inv sc1
	s_and_saveexec_b64 s[8:9], vcc
	s_cbranch_execz .LBB0_231
	s_bcnt1_i32_b64 s3, s[6:7]
	v_mov_b32_e32 v0, 0x2000
	v_mov_b32_e32 v1, s3
.LBB0_231:
	s_or_b64 exec, exec, s[8:9]
	s_waitcnt vmcnt(0)

.LBB0_296:
	s_or_b64 exec, exec, s[8:9]
	v_cvt_f32_u32_e32 v4, v2
	s_waitcnt vmcnt(0)
	v_readfirstlane_b32 s3, v3
	v_sub_u32_e32 v3, 0, v2
	v_rcp_iflag_f32_e32 v4, v4
	v_add_u32_e32 v5, s3, v1
	v_mul_f32_e32 v4, 0x4f7ffffe, v4
	v_cvt_u32_f32_e32 v4, v4
	v_mul_lo_u32 v1, v3, v4
	v_mul_hi_u32 v1, v4, v1
	v_add_u32_e32 v1, v4, v1
	v_mul_hi_u32 v1, v5, v1
	v_mul_lo_u32 v3, v1, v2
	v_sub_u32_e32 v3, v5, v3
	v_add_u32_e32 v4, 1, v1
	v_cmp_ge_u32_e32 vcc, v3, v2
	s_nop 1
	v_cndmask_b32_e32 v1, v1, v4, vcc
	v_sub_u32_e32 v4, v3, v2
	v_cndmask_b32_e32 v3, v3, v4, vcc
	v_add_u32_e32 v4, 1, v1
	v_cmp_ge_u32_e32 vcc, v3, v2
	v_add_u32_e32 v3, 1, v5
	s_nop 0
	v_cndmask_b32_e32 v1, v1, v4, vcc
	v_mul_lo_u32 v4, v2, v1
	v_add_u32_e32 v2, v4, v2
	v_cmp_ne_u32_e32 vcc, v3, v2
	s_and_saveexec_b64 s[6:7], vcc
	s_xor_b64 s[6:7], exec, s[6:7]
	s_cbranch_execz .LBB0_310
	s_waitcnt lgkmcnt(0)
	v_mov_b32_e32 v0, 0x35400
	global_load_dword v0, v0, s[28:29] offset:256 sc1
	s_add_u32 s24, s28, 0x35500
	s_addc_u32 s25, s29, 0
	s_waitcnt vmcnt(0)
	v_cmp_eq_u32_e32 vcc, v0, v1
	s_and_saveexec_b64 s[8:9], vcc
	s_cbranch_execz .LBB0_309
	s_add_u32 s12, s28, 0x32200
	s_addc_u32 s13, s29, 0
	s_mov_b32 s3, 1
	s_mov_b64 s[50:51], 0
	v_mov_b32_e32 v0, 0
	s_branch .LBB0_300

.LBB0_327:
	s_or_b64 exec, exec, s[6:7]
	s_mov_b64 s[6:7], exec
	v_mbcnt_lo_u32_b32 v0, s6, 0
	v_mbcnt_hi_u32_b32 v0, s7, v0
	v_cmp_eq_u32_e32 vcc, 0, v0
	s_waitcnt vmcnt(0)
	buffer_inv sc1
	s_and_saveexec_b64 s[8:9], vcc
	s_cbranch_execz .LBB0_329
	s_bcnt1_i32_b64 s3, s[6:7]
	v_mov_b32_e32 v0, 0x2000
	v_mov_b32_e32 v1, s3
.LBB0_329:
	s_or_b64 exec, exec, s[8:9]
	s_waitcnt vmcnt(0)

.LBB0_458:
	s_or_b64 exec, exec, s[6:7]
	s_mov_b64 s[6:7], exec
	v_mbcnt_lo_u32_b32 v0, s6, 0
	v_mbcnt_hi_u32_b32 v0, s7, v0
	v_cmp_eq_u32_e32 vcc, 0, v0
	s_waitcnt vmcnt(0)
	buffer_inv sc1
	s_and_saveexec_b64 s[8:9], vcc
	s_cbranch_execz .LBB0_460
	s_bcnt1_i32_b64 s3, s[6:7]
	v_mov_b32_e32 v0, 0x2000
	v_mov_b32_e32 v1, s3
.LBB0_460:
	s_or_b64 exec, exec, s[8:9]
	s_waitcnt vmcnt(0)

.LBB0_499:
	s_or_b64 exec, exec, s[12:13]
	v_cvt_f32_u32_e32 v4, v2
	s_waitcnt vmcnt(0)
	v_readfirstlane_b32 s3, v3
	v_sub_u32_e32 v3, 0, v2
	v_rcp_iflag_f32_e32 v4, v4
	v_add_u32_e32 v5, s3, v1
	v_mul_f32_e32 v4, 0x4f7ffffe, v4
	v_cvt_u32_f32_e32 v4, v4
	v_mul_lo_u32 v1, v3, v4
	v_mul_hi_u32 v1, v4, v1
	v_add_u32_e32 v1, v4, v1
	v_mul_hi_u32 v1, v5, v1
	v_mul_lo_u32 v3, v1, v2
	v_sub_u32_e32 v3, v5, v3
	v_add_u32_e32 v4, 1, v1
	v_cmp_ge_u32_e32 vcc, v3, v2
	s_nop 1
	v_cndmask_b32_e32 v1, v1, v4, vcc
	v_sub_u32_e32 v4, v3, v2
	v_cndmask_b32_e32 v3, v3, v4, vcc
	v_add_u32_e32 v4, 1, v1
	v_cmp_ge_u32_e32 vcc, v3, v2
	v_add_u32_e32 v3, 1, v5
	s_nop 0
	v_cndmask_b32_e32 v1, v1, v4, vcc
	v_mul_lo_u32 v4, v2, v1
	v_add_u32_e32 v2, v4, v2
	v_cmp_ne_u32_e32 vcc, v3, v2
	s_and_saveexec_b64 s[6:7], vcc
	s_xor_b64 s[6:7], exec, s[6:7]
	s_cbranch_execz .LBB0_513
	s_waitcnt lgkmcnt(0)
	v_mov_b32_e32 v0, 0x35400
	global_load_dword v0, v0, s[28:29] offset:256 sc1
	s_add_u32 s36, s28, 0x35500
	s_addc_u32 s37, s29, 0
	s_waitcnt vmcnt(0)
	v_cmp_eq_u32_e32 vcc, v0, v1
	s_and_saveexec_b64 s[12:13], vcc
	s_cbranch_execz .LBB0_512
	s_add_u32 s24, s28, 0x32200
	s_addc_u32 s25, s29, 0
	s_mov_b32 s3, 1
	s_mov_b64 s[44:45], 0
	v_mov_b32_e32 v0, 0
	s_branch .LBB0_503

.LBB0_530:
	s_or_b64 exec, exec, s[6:7]
	s_mov_b64 s[6:7], exec
	v_mbcnt_lo_u32_b32 v0, s6, 0
	v_mbcnt_hi_u32_b32 v0, s7, v0
	v_cmp_eq_u32_e32 vcc, 0, v0
	s_waitcnt vmcnt(0)
	buffer_inv sc1
	s_and_saveexec_b64 s[12:13], vcc
	s_cbranch_execz .LBB0_532
	s_bcnt1_i32_b64 s3, s[6:7]
	v_mov_b32_e32 v0, 0x2000
	v_mov_b32_e32 v1, s3
.LBB0_532:
	s_or_b64 exec, exec, s[12:13]
	s_waitcnt vmcnt(0)

.LBB0_568:
	s_or_b64 exec, exec, s[12:13]
	v_cvt_f32_u32_e32 v4, v2
	s_waitcnt vmcnt(0)
	v_readfirstlane_b32 s3, v3
	v_sub_u32_e32 v3, 0, v2
	v_rcp_iflag_f32_e32 v4, v4
	v_add_u32_e32 v5, s3, v1
	v_mul_f32_e32 v4, 0x4f7ffffe, v4
	v_cvt_u32_f32_e32 v4, v4
	v_mul_lo_u32 v1, v3, v4
	v_mul_hi_u32 v1, v4, v1
	v_add_u32_e32 v1, v4, v1
	v_mul_hi_u32 v1, v5, v1
	v_mul_lo_u32 v3, v1, v2
	v_sub_u32_e32 v3, v5, v3
	v_add_u32_e32 v4, 1, v1
	v_cmp_ge_u32_e32 vcc, v3, v2
	s_nop 1
	v_cndmask_b32_e32 v1, v1, v4, vcc
	v_sub_u32_e32 v4, v3, v2
	v_cndmask_b32_e32 v3, v3, v4, vcc
	v_add_u32_e32 v4, 1, v1
	v_cmp_ge_u32_e32 vcc, v3, v2
	v_add_u32_e32 v3, 1, v5
	s_nop 0
	v_cndmask_b32_e32 v1, v1, v4, vcc
	v_mul_lo_u32 v4, v2, v1
	v_add_u32_e32 v2, v4, v2
	v_cmp_ne_u32_e32 vcc, v3, v2
	s_and_saveexec_b64 s[6:7], vcc
	s_xor_b64 s[6:7], exec, s[6:7]
	s_cbranch_execz .LBB0_582
	s_waitcnt lgkmcnt(0)
	v_mov_b32_e32 v0, 0x35400
	global_load_dword v0, v0, s[28:29] offset:256 sc1
	s_add_u32 s50, s28, 0x35500
	s_addc_u32 s51, s29, 0
	s_waitcnt vmcnt(0)
	v_cmp_eq_u32_e32 vcc, v0, v1
	s_and_saveexec_b64 s[12:13], vcc
	s_cbranch_execz .LBB0_581
	s_add_u32 s44, s28, 0x32200
	s_addc_u32 s45, s29, 0
	s_mov_b32 s3, 1
	s_mov_b64 s[52:53], 0
	v_mov_b32_e32 v0, 0
	s_branch .LBB0_572

.LBB0_599:
	s_or_b64 exec, exec, s[6:7]
	s_mov_b64 s[6:7], exec
	v_mbcnt_lo_u32_b32 v0, s6, 0
	v_mbcnt_hi_u32_b32 v0, s7, v0
	v_cmp_eq_u32_e32 vcc, 0, v0
	s_waitcnt vmcnt(0)
	buffer_inv sc1
	s_and_saveexec_b64 s[12:13], vcc
	s_cbranch_execz .LBB0_601
	s_bcnt1_i32_b64 s3, s[6:7]
	v_mov_b32_e32 v0, 0x2000
	v_mov_b32_e32 v1, s3
.LBB0_601:
	s_or_b64 exec, exec, s[12:13]
	s_waitcnt vmcnt(0)

.LBB0_674:
	s_or_b64 exec, exec, s[12:13]
	v_cvt_f32_u32_e32 v4, v2
	s_waitcnt vmcnt(0)
	v_readfirstlane_b32 s3, v3
	v_sub_u32_e32 v3, 0, v2
	v_rcp_iflag_f32_e32 v4, v4
	v_add_u32_e32 v5, s3, v1
	v_mul_f32_e32 v4, 0x4f7ffffe, v4
	v_cvt_u32_f32_e32 v4, v4
	v_mul_lo_u32 v1, v3, v4
	v_mul_hi_u32 v1, v4, v1
	v_add_u32_e32 v1, v4, v1
	v_mul_hi_u32 v1, v5, v1
	v_mul_lo_u32 v3, v1, v2
	v_sub_u32_e32 v3, v5, v3
	v_add_u32_e32 v4, 1, v1
	v_cmp_ge_u32_e32 vcc, v3, v2
	s_nop 1
	v_cndmask_b32_e32 v1, v1, v4, vcc
	v_sub_u32_e32 v4, v3, v2
	v_cndmask_b32_e32 v3, v3, v4, vcc
	v_add_u32_e32 v4, 1, v1
	v_cmp_ge_u32_e32 vcc, v3, v2
	v_add_u32_e32 v3, 1, v5
	s_nop 0
	v_cndmask_b32_e32 v1, v1, v4, vcc
	v_mul_lo_u32 v4, v2, v1
	v_add_u32_e32 v2, v4, v2
	v_cmp_ne_u32_e32 vcc, v3, v2
	s_and_saveexec_b64 s[6:7], vcc
	s_xor_b64 s[6:7], exec, s[6:7]
	s_cbranch_execz .LBB0_688
	s_waitcnt lgkmcnt(0)
	v_mov_b32_e32 v0, 0x35400
	global_load_dword v0, v0, s[28:29] offset:256 sc1
	s_add_u32 s50, s28, 0x35500
	s_addc_u32 s51, s29, 0
	s_waitcnt vmcnt(0)
	v_cmp_eq_u32_e32 vcc, v0, v1
	s_and_saveexec_b64 s[12:13], vcc
	s_cbranch_execz .LBB0_687
	s_add_u32 s42, s28, 0x32200
	s_addc_u32 s43, s29, 0
	s_mov_b32 s3, 1
	s_mov_b64 s[52:53], 0
	v_mov_b32_e32 v0, 0
	s_branch .LBB0_678

.LBB0_705:
	s_or_b64 exec, exec, s[6:7]
	s_mov_b64 s[6:7], exec
	v_mbcnt_lo_u32_b32 v0, s6, 0
	v_mbcnt_hi_u32_b32 v0, s7, v0
	v_cmp_eq_u32_e32 vcc, 0, v0
	s_waitcnt vmcnt(0)
	buffer_inv sc1
	s_and_saveexec_b64 s[12:13], vcc
	s_cbranch_execz .LBB0_707
	s_bcnt1_i32_b64 s3, s[6:7]
	v_mov_b32_e32 v0, 0x2000
	v_mov_b32_e32 v1, s3
.LBB0_707:
	s_or_b64 exec, exec, s[12:13]
	s_waitcnt vmcnt(0)

.LBB0_777:
	s_or_b64 exec, exec, s[12:13]
	v_cvt_f32_u32_e32 v4, v2
	s_waitcnt vmcnt(0)
	v_readfirstlane_b32 s3, v3
	v_sub_u32_e32 v3, 0, v2
	v_rcp_iflag_f32_e32 v4, v4
	v_add_u32_e32 v5, s3, v1
	v_mul_f32_e32 v4, 0x4f7ffffe, v4
	v_cvt_u32_f32_e32 v4, v4
	v_mul_lo_u32 v1, v3, v4
	v_mul_hi_u32 v1, v4, v1
	v_add_u32_e32 v1, v4, v1
	v_mul_hi_u32 v1, v5, v1
	v_mul_lo_u32 v3, v1, v2
	v_sub_u32_e32 v3, v5, v3
	v_add_u32_e32 v4, 1, v1
	v_cmp_ge_u32_e32 vcc, v3, v2
	s_nop 1
	v_cndmask_b32_e32 v1, v1, v4, vcc
	v_sub_u32_e32 v4, v3, v2
	v_cndmask_b32_e32 v3, v3, v4, vcc
	v_add_u32_e32 v4, 1, v1
	v_cmp_ge_u32_e32 vcc, v3, v2
	v_add_u32_e32 v3, 1, v5
	s_nop 0
	v_cndmask_b32_e32 v1, v1, v4, vcc
	v_mul_lo_u32 v4, v2, v1
	v_add_u32_e32 v2, v4, v2
	v_cmp_ne_u32_e32 vcc, v3, v2
	s_and_saveexec_b64 s[8:9], vcc
	s_xor_b64 s[8:9], exec, s[8:9]
	s_cbranch_execz .LBB0_791
	s_waitcnt lgkmcnt(0)
	v_mov_b32_e32 v0, 0x35400
	global_load_dword v0, v0, s[28:29] offset:256 sc1
	s_add_u32 s16, s28, 0x35500
	s_addc_u32 s17, s29, 0
	s_waitcnt vmcnt(0)
	v_cmp_eq_u32_e32 vcc, v0, v1
	s_and_saveexec_b64 s[12:13], vcc
	s_cbranch_execz .LBB0_790
	s_add_u32 s14, s28, 0x32200
	s_addc_u32 s15, s29, 0
	s_mov_b32 s3, 1
	s_mov_b64 s[40:41], 0
	v_mov_b32_e32 v0, 0
	s_branch .LBB0_781

.LBB0_808:
	s_or_b64 exec, exec, s[8:9]
	s_mov_b64 s[8:9], exec
	v_mbcnt_lo_u32_b32 v0, s8, 0
	v_mbcnt_hi_u32_b32 v0, s9, v0
	v_cmp_eq_u32_e32 vcc, 0, v0
	s_waitcnt vmcnt(0)
	buffer_inv sc1
	s_and_saveexec_b64 s[12:13], vcc
	s_cbranch_execz .LBB0_810
	s_bcnt1_i32_b64 s3, s[8:9]
	v_mov_b32_e32 v0, 0x2000
	v_mov_b32_e32 v1, s3
.LBB0_810:
	s_or_b64 exec, exec, s[12:13]
	s_waitcnt vmcnt(0)

.LBB0_874:
	s_or_b64 exec, exec, s[8:9]
	s_mov_b64 s[8:9], exec
	v_mbcnt_lo_u32_b32 v0, s8, 0
	v_mbcnt_hi_u32_b32 v0, s9, v0
	v_cmp_eq_u32_e32 vcc, 0, v0
	s_waitcnt vmcnt(0)
	buffer_inv sc1
	s_and_saveexec_b64 s[12:13], vcc
	s_cbranch_execz .LBB0_876
	s_bcnt1_i32_b64 s3, s[8:9]
	v_mov_b32_e32 v0, 0x2000
	v_mov_b32_e32 v1, s3
.LBB0_876:
	s_or_b64 exec, exec, s[12:13]
	s_waitcnt vmcnt(0)

.LBB0_916:
	s_or_b64 exec, exec, s[12:13]
	v_cvt_f32_u32_e32 v4, v2
	s_waitcnt vmcnt(0)
	v_readfirstlane_b32 s3, v3
	v_sub_u32_e32 v3, 0, v2
	v_rcp_iflag_f32_e32 v4, v4
	v_add_u32_e32 v5, s3, v1
	v_mul_f32_e32 v4, 0x4f7ffffe, v4
	v_cvt_u32_f32_e32 v4, v4
	v_mul_lo_u32 v1, v3, v4
	v_mul_hi_u32 v1, v4, v1
	v_add_u32_e32 v1, v4, v1
	v_mul_hi_u32 v1, v5, v1
	v_mul_lo_u32 v3, v1, v2
	v_sub_u32_e32 v3, v5, v3
	v_add_u32_e32 v4, 1, v1
	v_cmp_ge_u32_e32 vcc, v3, v2
	s_nop 1
	v_cndmask_b32_e32 v1, v1, v4, vcc
	v_sub_u32_e32 v4, v3, v2
	v_cndmask_b32_e32 v3, v3, v4, vcc
	v_add_u32_e32 v4, 1, v1
	v_cmp_ge_u32_e32 vcc, v3, v2
	v_add_u32_e32 v3, 1, v5
	s_nop 0
	v_cndmask_b32_e32 v1, v1, v4, vcc
	v_mul_lo_u32 v4, v2, v1
	v_add_u32_e32 v2, v4, v2
	v_cmp_ne_u32_e32 vcc, v3, v2
	s_and_saveexec_b64 s[8:9], vcc
	s_xor_b64 s[8:9], exec, s[8:9]
	s_cbranch_execz .LBB0_930
	s_waitcnt lgkmcnt(0)
	v_mov_b32_e32 v0, 0x35400
	global_load_dword v0, v0, s[28:29] offset:256 sc1
	s_add_u32 s16, s28, 0x35500
	s_addc_u32 s17, s29, 0
	s_waitcnt vmcnt(0)
	v_cmp_eq_u32_e32 vcc, v0, v1
	s_and_saveexec_b64 s[12:13], vcc
	s_cbranch_execz .LBB0_929
	s_add_u32 s14, s28, 0x32200
	s_addc_u32 s15, s29, 0
	s_mov_b32 s3, 1
	s_mov_b64 s[22:23], 0
	v_mov_b32_e32 v0, 0
	s_branch .LBB0_920

.LBB0_947:
	s_or_b64 exec, exec, s[8:9]
	s_mov_b64 s[8:9], exec
	v_mbcnt_lo_u32_b32 v0, s8, 0
	v_mbcnt_hi_u32_b32 v0, s9, v0
	v_cmp_eq_u32_e32 vcc, 0, v0
	s_waitcnt vmcnt(0)
	buffer_inv sc1
	s_and_saveexec_b64 s[12:13], vcc
	s_cbranch_execz .LBB0_949
	s_bcnt1_i32_b64 s3, s[8:9]
	v_mov_b32_e32 v0, 0x2000
	v_mov_b32_e32 v1, s3
.LBB0_949:
	s_or_b64 exec, exec, s[12:13]
	s_waitcnt vmcnt(0)

.LBB0_988:
	s_or_b64 exec, exec, s[8:9]
	v_cvt_f32_u32_e32 v4, v2
	s_waitcnt vmcnt(0)
	v_readfirstlane_b32 s3, v3
	v_sub_u32_e32 v3, 0, v2
	v_rcp_iflag_f32_e32 v4, v4
	v_add_u32_e32 v5, s3, v1
	v_mul_f32_e32 v4, 0x4f7ffffe, v4
	v_cvt_u32_f32_e32 v4, v4
	v_mul_lo_u32 v1, v3, v4
	v_mul_hi_u32 v1, v4, v1
	v_add_u32_e32 v1, v4, v1
	v_mul_hi_u32 v1, v5, v1
	v_mul_lo_u32 v3, v1, v2
	v_sub_u32_e32 v3, v5, v3
	v_add_u32_e32 v4, 1, v1
	v_cmp_ge_u32_e32 vcc, v3, v2
	s_nop 1
	v_cndmask_b32_e32 v1, v1, v4, vcc
	v_sub_u32_e32 v4, v3, v2
	v_cndmask_b32_e32 v3, v3, v4, vcc
	v_add_u32_e32 v4, 1, v1
	v_cmp_ge_u32_e32 vcc, v3, v2
	v_add_u32_e32 v3, 1, v5
	s_nop 0
	v_cndmask_b32_e32 v1, v1, v4, vcc
	v_mul_lo_u32 v4, v2, v1
	v_add_u32_e32 v2, v4, v2
	v_cmp_ne_u32_e32 vcc, v3, v2
	s_and_saveexec_b64 s[6:7], vcc
	s_xor_b64 s[6:7], exec, s[6:7]
	s_cbranch_execz .LBB0_1002
	s_waitcnt lgkmcnt(0)
	v_mov_b32_e32 v0, 0x35400
	global_load_dword v0, v0, s[28:29] offset:256 sc1
	s_add_u32 s12, s28, 0x35500
	s_addc_u32 s13, s29, 0
	s_waitcnt vmcnt(0)
	v_cmp_eq_u32_e32 vcc, v0, v1
	s_and_saveexec_b64 s[8:9], vcc
	s_cbranch_execz .LBB0_1001
	s_add_u32 s10, s28, 0x32200
	s_addc_u32 s11, s29, 0
	s_mov_b32 s3, 1
	s_mov_b64 s[14:15], 0
	v_mov_b32_e32 v0, 0
	s_branch .LBB0_992

.LBB0_1019:
	s_or_b64 exec, exec, s[6:7]
	s_mov_b64 s[6:7], exec
	v_mbcnt_lo_u32_b32 v0, s6, 0
	v_mbcnt_hi_u32_b32 v0, s7, v0
	v_cmp_eq_u32_e32 vcc, 0, v0
	s_waitcnt vmcnt(0)
	buffer_inv sc1
	s_and_saveexec_b64 s[8:9], vcc
	s_cbranch_execz .LBB0_1021
	s_bcnt1_i32_b64 s3, s[6:7]
	v_mov_b32_e32 v0, 0x2000
	v_mov_b32_e32 v1, s3
.LBB0_1021:
	s_or_b64 exec, exec, s[8:9]
	s_waitcnt vmcnt(0)
